# adds: xatt K/V staging 16 loads in flight (was serial); x->bf16 init loop 4x unrolled (8 loads in flight per lane); stacked on previous
# speedup vs baseline: 1.0001x; 1.0001x over previous
; __device__ __forceinline__ u32x4 pack8(const f32x4 a, const f32x4 b) { u32x4 w; w.x = cvt_pk_bf16(a[0], a[1]); w.y = cvt_pk_bf16(a[2], a[3]); w.z = cvt_pk_bf16(b[0], b[1]); w.w = cvt_pk_bf16(b[2], b[3]); return w; }
; __device__ __forceinline__ void cvt_bf16(const float* __restrict__ src, bf16_t* __restrict__ dst, size_t n, const int tid, const int bid) {
;     for (size_t i = ((size_t)bid * 512 + tid) * 8; i < n; i += (size_t)gridDim.x * 512 * 8) {
;         const f32x4 a = *(const f32x4*)(src + i), b = *(const f32x4*)(src + i + 4);
;         *(u32x4*)(dst + i) = pack8(a, b);
;     }
; }
.Lcvt4_head:
	v_lshl_add_u64 v[62:63], s[6:7], 1, v[12:13]
	v_lshl_add_u64 v[62:63], v[62:63], 0, s[6:7]
	v_cmp_ge_u64_e32 vcc, s[14:15], v[62:63]
	s_nop 1
	s_cmp_eq_u64 vcc, exec
	s_cbranch_scc0 .LBB0_9
	global_load_dwordx4 v[14:17], v[8:9], off offset:-16
	global_load_dwordx4 v[18:21], v[8:9], off
	v_lshl_add_u64 v[64:65], v[8:9], 0, s[8:9]
	global_load_dwordx4 v[30:33], v[64:65], off offset:-16
	global_load_dwordx4 v[34:37], v[64:65], off
	v_lshl_add_u64 v[64:65], v[64:65], 0, s[8:9]
	global_load_dwordx4 v[38:41], v[64:65], off offset:-16
	global_load_dwordx4 v[42:45], v[64:65], off
	v_lshl_add_u64 v[64:65], v[64:65], 0, s[8:9]
	global_load_dwordx4 v[46:49], v[64:65], off offset:-16
	global_load_dwordx4 v[50:53], v[64:65], off
	v_lshl_add_u64 v[8:9], v[64:65], 0, s[8:9]
	v_lshl_add_u64 v[12:13], s[6:7], 2, v[12:13]
	v_cmp_lt_u64_e32 vcc, s[14:15], v[12:13]
	s_nop 1
	s_or_b64 s[12:13], vcc, s[12:13]
	s_waitcnt vmcnt(6)
	v_cvt_pk_bf16_f32 v14, v14, v15
	v_cvt_pk_bf16_f32 v15, v16, v17
	v_cvt_pk_bf16_f32 v16, v18, v19
	v_cvt_pk_bf16_f32 v17, v20, v21
	global_store_dwordx4 v[10:11], v[14:17], off
	v_lshl_add_u64 v[10:11], v[10:11], 0, s[10:11]
	s_waitcnt vmcnt(5)
	v_cvt_pk_bf16_f32 v30, v30, v31
	v_cvt_pk_bf16_f32 v31, v32, v33
	v_cvt_pk_bf16_f32 v32, v34, v35
	v_cvt_pk_bf16_f32 v33, v36, v37
	global_store_dwordx4 v[10:11], v[30:33], off
	v_lshl_add_u64 v[10:11], v[10:11], 0, s[10:11]
	s_waitcnt vmcnt(4)
	v_cvt_pk_bf16_f32 v38, v38, v39
	v_cvt_pk_bf16_f32 v39, v40, v41
	v_cvt_pk_bf16_f32 v40, v42, v43
	v_cvt_pk_bf16_f32 v41, v44, v45
	global_store_dwordx4 v[10:11], v[38:41], off
	v_lshl_add_u64 v[10:11], v[10:11], 0, s[10:11]
	s_waitcnt vmcnt(3)
	v_cvt_pk_bf16_f32 v46, v46, v47
	v_cvt_pk_bf16_f32 v47, v48, v49
	v_cvt_pk_bf16_f32 v48, v50, v51
	v_cvt_pk_bf16_f32 v49, v52, v53
	global_store_dwordx4 v[10:11], v[46:49], off
	v_lshl_add_u64 v[10:11], v[10:11], 0, s[10:11]
	s_andn2_b64 exec, exec, s[12:13]
	s_cbranch_execnz .Lcvt4_head
	s_branch .LBB0_10

; #define LAS __attribute__((address_space(3)))
; __device__ __forceinline__ void xatt_phase(const bf16_t* xq, const bf16_t* xk, const bf16_t* xvt, bf16_t* xo, LAS unsigned char* lds, const int tid, const int bid) {
;     ...
;         const bf16_t* kbase = xk + (size_t)(b * 256) * XW + xh * 128; const bf16_t* vtbase = xvt + (size_t)(xh * 128) * MROWS + b * 256;
; #pragma unroll
;         for (int i = 0; i < 8; ++i) {
;             const int key = (tid >> 4) + 32 * i, d8 = (tid & 15) * 8;
;             *(LAS u32x4*)(Kl + key * KP + d8 * 2) = *(const u32x4*)(kbase + (size_t)key * XW + d8);
;         }
; #pragma unroll
;         for (int i = 0; i < 8; ++i) {
;             const int d = tid >> 2, c = 4 * i + (tid & 3);
;             *(LAS u32x4*)(Vt + d * VP + c * 16) = *(const u32x4*)(vtbase + (size_t)d * MROWS + c * 8);
;         }
;         __syncthreads();
.LBB0_236:
	s_lshl_b32 s0, s12, 5
	s_and_b32 s0, s0, 0xe0
	s_ashr_i32 s1, s12, 3
	s_add_i32 s2, s0, s1
	v_readlane_b32 s0, v250, 36
	v_readlane_b32 s1, v250, 37
	s_and_b64 s[0:1], s[0:1], exec
	s_cselect_b32 s13, s2, s12
	s_ashr_i32 s0, s13, 6
	s_lshl_b32 s4, s0, 8
	s_ashr_i32 s5, s4, 31
	s_lshl_b64 s[14:15], s[4:5], 10
	v_readlane_b32 s16, v251, 49
	v_readlane_b32 s17, v251, 50
	s_add_u32 s1, s16, s14
	s_addc_u32 s15, s17, s15
	s_lshl_b32 s2, s13, 3
	s_and_b32 s16, s2, 0x180
	s_lshl_b32 s2, s16, 1
	s_add_u32 s14, s1, s2
	s_addc_u32 s15, s15, 0
	v_lshl_add_u64 v[6:7], s[14:15], 0, v[0:1]
	v_lshl_add_u64 v[72:73], v[6:7], 0, v[86:87]
	global_load_dwordx4 v[8:11], v[72:73], off
	s_lshl_b32 s1, s16, 11
	s_add_u32 s1, s6, s1
	s_addc_u32 s16, s7, 0
	s_lshl_b64 s[4:5], s[4:5], 1
	s_add_u32 s4, s1, s4
	s_addc_u32 s5, s16, s5
	v_mov_b32_e32 v103, v1
	v_mov_b32_e32 v105, v1
	v_mov_b32_e32 v107, v1
	v_mov_b32_e32 v109, v1
	v_mov_b32_e32 v111, v1
	v_mov_b32_e32 v113, v1
	v_mov_b32_e32 v115, v1
	v_mov_b32_e32 v117, v1
	s_ashr_i32 s1, s0, 31
	s_lshl_b64 s[0:1], s[0:1], 12
	v_lshl_add_u64 v[120:121], v[82:83], 0, s[2:3]
	v_lshl_add_u64 v[122:123], v[84:85], 0, s[2:3]
	v_lshl_add_u64 v[72:73], v[6:7], 0, v[88:89]
	global_load_dwordx4 v[12:15], v[72:73], off
	v_lshl_add_u64 v[72:73], v[6:7], 0, v[90:91]
	global_load_dwordx4 v[16:19], v[72:73], off
	v_lshl_add_u64 v[72:73], v[6:7], 0, v[92:93]
	global_load_dwordx4 v[20:23], v[72:73], off
	v_lshl_add_u64 v[72:73], v[6:7], 0, v[94:95]
	global_load_dwordx4 v[24:27], v[72:73], off
	v_lshl_add_u64 v[72:73], v[6:7], 0, v[96:97]
	global_load_dwordx4 v[28:31], v[72:73], off
	v_lshl_add_u64 v[72:73], v[6:7], 0, v[98:99]
	global_load_dwordx4 v[32:35], v[72:73], off
	v_lshl_add_u64 v[72:73], v[6:7], 0, v[100:101]
	global_load_dwordx4 v[36:39], v[72:73], off
	v_lshl_add_u64 v[6:7], s[4:5], 0, v[78:79]
	s_lshl_b32 s4, s13, 8
	s_and_b32 s4, s4, 0xf00
	s_or_b32 s0, s0, s4
	v_lshl_add_u64 v[118:119], s[0:1], 0, v[80:81]
	s_mov_b64 s[4:5], 0
	s_mov_b64 s[0:1], -1
	v_lshl_add_u64 v[72:73], v[6:7], 0, v[102:103]
	global_load_dwordx4 v[40:43], v[72:73], off
	v_lshl_add_u64 v[72:73], v[6:7], 0, v[104:105]
	global_load_dwordx4 v[44:47], v[72:73], off
	v_lshl_add_u64 v[72:73], v[6:7], 0, v[106:107]
	global_load_dwordx4 v[48:51], v[72:73], off
	v_lshl_add_u64 v[72:73], v[6:7], 0, v[108:109]
	global_load_dwordx4 v[52:55], v[72:73], off
	v_lshl_add_u64 v[72:73], v[6:7], 0, v[110:111]
	global_load_dwordx4 v[56:59], v[72:73], off
	v_lshl_add_u64 v[72:73], v[6:7], 0, v[112:113]
	global_load_dwordx4 v[60:63], v[72:73], off
	v_lshl_add_u64 v[72:73], v[6:7], 0, v[114:115]
	global_load_dwordx4 v[64:67], v[72:73], off
	v_lshl_add_u64 v[72:73], v[6:7], 0, v[116:117]
	global_load_dwordx4 v[68:71], v[72:73], off
	s_waitcnt vmcnt(0) lgkmcnt(0)
	ds_write_b128 v128, v[8:11]
	ds_write_b128 v128, v[12:15] offset:8704
	ds_write_b128 v128, v[16:19] offset:17408
	ds_write_b128 v128, v[20:23] offset:26112
	ds_write_b128 v128, v[24:27] offset:34816
	ds_write_b128 v128, v[28:31] offset:43520
	ds_write_b128 v128, v[32:35] offset:52224
	ds_write_b128 v128, v[36:39] offset:60928
	ds_write_b128 v129, v[40:43]
	ds_write_b128 v130, v[44:47]
	ds_write_b128 v131, v[48:51]
	ds_write_b128 v132, v[52:55]
	ds_write_b128 v133, v[56:59]
	ds_write_b128 v134, v[60:63]
	ds_write_b128 v135, v[64:67]
	ds_write_b128 v136, v[68:71]
	s_waitcnt lgkmcnt(0)
	s_barrier
